# LayerNorm sample rows: one dword per cache line of the residual and partial-sum rows is touched while chunk 0 loads are in flight so chunks 1..7 hit in cache
# baseline (speedup 1.0000x reference)
.LBB0_1535:
	v_add_u32_e32 v96, 0xffffe000, v117
	v_lshlrev_b64 v[64:65], 11, v[96:97]
	v_or_b32_e32 v64, v64, v98
	v_readlane_b32 s36, v253, 21
	s_movk_i32 s0, 0x1fff
	v_lshlrev_b64 v[104:105], 2, v[64:65]
	v_readlane_b32 s38, v253, 23
	v_readlane_b32 s39, v253, 24
	v_cmp_lt_i32_e64 s[0:1], s0, v117
	v_readlane_b32 s37, v253, 22
	v_lshl_add_u64 v[80:81], s[38:39], 0, v[104:105]
	v_readlane_b32 s40, v253, 25
	v_readlane_b32 s41, v253, 26
	v_readlane_b32 s42, v253, 27
	v_readlane_b32 s43, v253, 28
	v_readlane_b32 s44, v253, 29
	v_readlane_b32 s45, v253, 30
	v_readlane_b32 s46, v253, 31
	v_readlane_b32 s47, v253, 32
	v_readlane_b32 s48, v253, 33
	v_readlane_b32 s49, v253, 34
	v_readlane_b32 s50, v253, 35
	v_readlane_b32 s51, v253, 36
	s_and_saveexec_b64 s[12:13], s[0:1]
	s_xor_b64 s[12:13], exec, s[12:13]
	s_cbranch_execz .LBB0_1537
	v_lshl_add_u64 v[72:73], s[92:93], 0, v[104:105]
	global_load_dwordx4 v[64:67], v[80:81], off
	global_load_dwordx4 v[148:151], v[72:73], off
	v_add_co_u32_e32 v146, vcc, 0x200000, v72
	s_nop 1
	v_addc_co_u32_e32 v147, vcc, 0, v73, vcc
	global_load_dwordx4 v[152:155], v[146:147], off
	v_add_co_u32_e32 v146, vcc, 0x400000, v72
	s_nop 1
	v_addc_co_u32_e32 v147, vcc, 0, v73, vcc
	global_load_dwordx4 v[156:159], v[146:147], off
	v_add_co_u32_e32 v146, vcc, 0x600000, v72
	s_nop 1
	v_addc_co_u32_e32 v147, vcc, 0, v73, vcc
	global_load_dwordx4 v[160:163], v[146:147], off
	v_add_co_u32_e32 v146, vcc, 0x800000, v72
	s_nop 1
	v_addc_co_u32_e32 v147, vcc, 0, v73, vcc
	global_load_dwordx4 v[164:167], v[146:147], off
	v_add_co_u32_e32 v146, vcc, 0xa00000, v72
	s_nop 1
	v_addc_co_u32_e32 v147, vcc, 0, v73, vcc
	global_load_dwordx4 v[168:171], v[146:147], off
	v_add_co_u32_e32 v146, vcc, 0xc00000, v72
	s_nop 1
	v_addc_co_u32_e32 v147, vcc, 0, v73, vcc
	global_load_dwordx4 v[172:175], v[146:147], off
	v_add_co_u32_e32 v146, vcc, 0xe00000, v72
	s_nop 1
	v_addc_co_u32_e32 v147, vcc, 0, v73, vcc
	global_load_dwordx4 v[176:179], v[146:147], off
	v_and_b32_e32 v192, 63, v230
	v_mul_u32_u24_e32 v194, 0x70, v192
	v_mov_b32_e32 v195, 0
	v_lshl_add_u64 v[198:199], v[72:73], 0, v[194:195]
	s_mov_b64 s[100:101], 0x200000
	global_load_dword v193, v[198:199], off
	v_lshl_add_u64 v[198:199], v[198:199], 0, s[100:101]
	global_load_dword v193, v[198:199], off
	v_lshl_add_u64 v[198:199], v[198:199], 0, s[100:101]
	global_load_dword v193, v[198:199], off
	v_lshl_add_u64 v[198:199], v[198:199], 0, s[100:101]
	global_load_dword v193, v[198:199], off
	v_lshl_add_u64 v[198:199], v[198:199], 0, s[100:101]
	global_load_dword v193, v[198:199], off
	v_lshl_add_u64 v[198:199], v[198:199], 0, s[100:101]
	global_load_dword v193, v[198:199], off
	v_lshl_add_u64 v[198:199], v[198:199], 0, s[100:101]
	global_load_dword v193, v[198:199], off
	v_lshl_add_u64 v[198:199], v[198:199], 0, s[100:101]
	global_load_dword v193, v[198:199], off
	v_lshl_add_u64 v[196:197], v[80:81], 0, v[194:195]
	global_load_dword v193, v[196:197], off
	s_waitcnt vmcnt(0)
	v_pk_fma_f32 v[68:69], v[64:65], s[6:7], v[148:149] op_sel_hi:[1,0,1]
	v_pk_fma_f32 v[70:71], v[66:67], s[6:7], v[150:151] op_sel_hi:[1,0,1]
	v_pk_add_f32 v[68:69], v[68:69], v[152:153]
	v_pk_add_f32 v[70:71], v[70:71], v[154:155]
	v_pk_add_f32 v[68:69], v[68:69], v[156:157]
	v_pk_add_f32 v[70:71], v[70:71], v[158:159]
	v_pk_add_f32 v[68:69], v[68:69], v[160:161]
	v_pk_add_f32 v[70:71], v[70:71], v[162:163]
	v_pk_add_f32 v[68:69], v[68:69], v[164:165]
	v_pk_add_f32 v[70:71], v[70:71], v[166:167]
	v_pk_add_f32 v[68:69], v[68:69], v[168:169]
	v_pk_add_f32 v[70:71], v[70:71], v[170:171]
	v_pk_add_f32 v[68:69], v[68:69], v[172:173]
	v_pk_add_f32 v[70:71], v[70:71], v[174:175]
	v_pk_add_f32 v[66:67], v[70:71], v[178:179]
	v_pk_add_f32 v[64:65], v[68:69], v[176:177]
	s_or_saveexec_b64 s[12:13], s[12:13]
	v_lshl_add_u64 v[106:107], s[96:97], 0, v[100:101]
	s_xor_b64 exec, exec, s[12:13]
	s_cbranch_execz .LBB0_1539
	s_branch .LBB0_1538

.LBB0_2069:
	v_add_u32_e32 v96, 0xffffe000, v117
	s_movk_i32 s2, 0x1fff
	v_lshlrev_b64 v[104:105], 11, v[96:97]
	v_cmp_lt_i32_e64 s[34:35], s2, v117
	v_or_b32_e32 v104, v104, v98
	s_and_saveexec_b64 s[2:3], s[34:35]
	s_xor_b64 s[2:3], exec, s[2:3]
	s_cbranch_execz .LBB0_2071
	v_lshl_add_u64 v[64:65], v[104:105], 1, s[82:83]
	global_load_dwordx2 v[64:65], v[64:65], off
	v_lshl_add_u64 v[72:73], v[104:105], 2, s[84:85]
	global_load_dwordx4 v[148:151], v[72:73], off
	v_add_co_u32_e32 v146, vcc, 0x200000, v72
	s_nop 1
	v_addc_co_u32_e32 v147, vcc, 0, v73, vcc
	global_load_dwordx4 v[152:155], v[146:147], off
	v_and_b32_e32 v192, 63, v230
	v_mul_u32_u24_e32 v194, 0x70, v192
	v_mov_b32_e32 v195, 0
	v_lshl_add_u64 v[198:199], v[72:73], 0, v[194:195]
	s_mov_b64 s[100:101], 0x200000
	global_load_dword v193, v[198:199], off
	v_lshl_add_u64 v[198:199], v[198:199], 0, s[100:101]
	global_load_dword v193, v[198:199], off
	v_mul_u32_u24_e32 v194, 56, v192
	v_lshl_add_u64 v[196:197], v[104:105], 1, s[82:83]
	v_lshl_add_u64 v[196:197], v[196:197], 0, v[194:195]
	global_load_dword v193, v[196:197], off
	s_waitcnt vmcnt(0)
	v_lshlrev_b32_e32 v68, 16, v64
	v_and_b32_e32 v69, 0xffff0000, v64
	v_lshlrev_b32_e32 v70, 16, v65
	v_and_b32_e32 v71, 0xffff0000, v65
	v_pk_fma_f32 v[68:69], v[68:69], s[92:93], v[148:149] op_sel_hi:[1,0,1]
	v_pk_fma_f32 v[70:71], v[70:71], s[92:93], v[150:151] op_sel_hi:[1,0,1]
	v_pk_add_f32 v[66:67], v[154:155], v[70:71]
	v_pk_add_f32 v[64:65], v[152:153], v[68:69]
	s_or_saveexec_b64 s[2:3], s[2:3]
	v_lshl_add_u64 v[106:107], s[96:97], 0, v[100:101]
	s_xor_b64 exec, exec, s[2:3]
	s_cbranch_execz .LBB0_2073
	s_branch .LBB0_2072

.LBB0_2489:
	v_add_u32_e32 v96, 0xffffe000, v123
	s_movk_i32 s0, 0x1fff
	v_lshlrev_b64 v[106:107], 11, v[96:97]
	v_cmp_lt_i32_e64 s[0:1], s0, v123
	v_or_b32_e32 v106, v106, v98
	s_and_saveexec_b64 s[4:5], s[0:1]
	s_xor_b64 s[4:5], exec, s[4:5]
	s_cbranch_execz .LBB0_2491
	v_lshl_add_u64 v[64:65], v[106:107], 1, s[82:83]
	global_load_dwordx2 v[64:65], v[64:65], off
	v_lshl_add_u64 v[72:73], v[106:107], 2, s[84:85]
	global_load_dwordx4 v[148:151], v[72:73], off
	v_add_co_u32_e32 v146, vcc, s12, v72
	s_nop 1
	v_addc_co_u32_e32 v147, vcc, 0, v73, vcc
	global_load_dwordx4 v[152:155], v[146:147], off
	v_add_co_u32_e32 v146, vcc, s13, v72
	s_nop 1
	v_addc_co_u32_e32 v147, vcc, 0, v73, vcc
	global_load_dwordx4 v[156:159], v[146:147], off
	v_add_co_u32_e32 v146, vcc, s14, v72
	s_nop 1
	v_addc_co_u32_e32 v147, vcc, 0, v73, vcc
	global_load_dwordx4 v[160:163], v[146:147], off
	v_add_co_u32_e32 v146, vcc, s15, v72
	s_nop 1
	v_addc_co_u32_e32 v147, vcc, 0, v73, vcc
	global_load_dwordx4 v[164:167], v[146:147], off
	v_add_co_u32_e32 v146, vcc, s16, v72
	s_nop 1
	v_addc_co_u32_e32 v147, vcc, 0, v73, vcc
	global_load_dwordx4 v[168:171], v[146:147], off
	v_add_co_u32_e32 v146, vcc, s17, v72
	s_nop 1
	v_addc_co_u32_e32 v147, vcc, 0, v73, vcc
	global_load_dwordx4 v[172:175], v[146:147], off
	v_add_co_u32_e32 v146, vcc, s18, v72
	s_nop 1
	v_addc_co_u32_e32 v147, vcc, 0, v73, vcc
	global_load_dwordx4 v[176:179], v[146:147], off
	v_add_co_u32_e32 v146, vcc, s19, v72
	s_nop 1
	v_addc_co_u32_e32 v147, vcc, 0, v73, vcc
	global_load_dwordx4 v[180:183], v[146:147], off
	v_add_co_u32_e32 v146, vcc, s20, v72
	s_nop 1
	v_addc_co_u32_e32 v147, vcc, 0, v73, vcc
	global_load_dwordx4 v[184:187], v[146:147], off
	v_add_co_u32_e32 v146, vcc, 0x1400000, v72
	s_nop 1
	v_addc_co_u32_e32 v147, vcc, 0, v73, vcc
	global_load_dwordx4 v[188:191], v[146:147], off
	v_and_b32_e32 v192, 63, v230
	v_mul_u32_u24_e32 v194, 0x70, v192
	v_mov_b32_e32 v195, 0
	v_lshl_add_u64 v[198:199], v[72:73], 0, v[194:195]
	s_mov_b64 s[100:101], 0x200000
	global_load_dword v193, v[198:199], off
	v_lshl_add_u64 v[198:199], v[198:199], 0, s[100:101]
	global_load_dword v193, v[198:199], off
	v_lshl_add_u64 v[198:199], v[198:199], 0, s[100:101]
	global_load_dword v193, v[198:199], off
	v_lshl_add_u64 v[198:199], v[198:199], 0, s[100:101]
	global_load_dword v193, v[198:199], off
	v_lshl_add_u64 v[198:199], v[198:199], 0, s[100:101]
	global_load_dword v193, v[198:199], off
	v_lshl_add_u64 v[198:199], v[198:199], 0, s[100:101]
	global_load_dword v193, v[198:199], off
	v_lshl_add_u64 v[198:199], v[198:199], 0, s[100:101]
	global_load_dword v193, v[198:199], off
	v_lshl_add_u64 v[198:199], v[198:199], 0, s[100:101]
	global_load_dword v193, v[198:199], off
	v_lshl_add_u64 v[198:199], v[198:199], 0, s[100:101]
	global_load_dword v193, v[198:199], off
	v_lshl_add_u64 v[198:199], v[198:199], 0, s[100:101]
	global_load_dword v193, v[198:199], off
	v_lshl_add_u64 v[198:199], v[198:199], 0, s[100:101]
	global_load_dword v193, v[198:199], off
	v_mul_u32_u24_e32 v194, 56, v192
	v_lshl_add_u64 v[196:197], v[106:107], 1, s[82:83]
	v_lshl_add_u64 v[196:197], v[196:197], 0, v[194:195]
	global_load_dword v193, v[196:197], off
	s_waitcnt vmcnt(0)
	v_lshlrev_b32_e32 v68, 16, v64
	v_and_b32_e32 v69, 0xffff0000, v64
	v_lshlrev_b32_e32 v70, 16, v65
	v_and_b32_e32 v71, 0xffff0000, v65
	v_pk_fma_f32 v[68:69], v[68:69], s[92:93], v[148:149] op_sel_hi:[1,0,1]
	v_pk_fma_f32 v[70:71], v[70:71], s[92:93], v[150:151] op_sel_hi:[1,0,1]
	v_pk_add_f32 v[68:69], v[152:153], v[68:69]
	v_pk_add_f32 v[70:71], v[154:155], v[70:71]
	v_pk_add_f32 v[68:69], v[156:157], v[68:69]
	v_pk_add_f32 v[70:71], v[158:159], v[70:71]
	v_pk_add_f32 v[68:69], v[160:161], v[68:69]
	v_pk_add_f32 v[70:71], v[162:163], v[70:71]
	v_pk_add_f32 v[68:69], v[164:165], v[68:69]
	v_pk_add_f32 v[70:71], v[166:167], v[70:71]
	v_pk_add_f32 v[68:69], v[168:169], v[68:69]
	v_pk_add_f32 v[70:71], v[170:171], v[70:71]
	v_pk_add_f32 v[68:69], v[172:173], v[68:69]
	v_pk_add_f32 v[70:71], v[174:175], v[70:71]
	v_pk_add_f32 v[68:69], v[176:177], v[68:69]
	v_pk_add_f32 v[70:71], v[178:179], v[70:71]
	v_pk_add_f32 v[68:69], v[180:181], v[68:69]
	v_pk_add_f32 v[70:71], v[182:183], v[70:71]
	v_pk_add_f32 v[68:69], v[184:185], v[68:69]
	v_pk_add_f32 v[70:71], v[186:187], v[70:71]
	v_pk_add_f32 v[66:67], v[190:191], v[70:71]
	v_pk_add_f32 v[64:65], v[188:189], v[68:69]
	s_or_saveexec_b64 s[4:5], s[4:5]
	v_lshl_add_u64 v[108:109], v[102:103], 0, v[100:101]
	s_xor_b64 exec, exec, s[4:5]
	s_cbranch_execz .LBB0_2493
	s_branch .LBB0_2492
